# EpiResid (out-proj/down-proj): residual loads for the first two rows of the second half issued at epilogue start into spare VGPRs
# speedup vs baseline: 1.0104x; 1.0042x over previous
.LBB0_777:
	v_lshl_or_b32 v166, s18, 8, v193
	v_lshl_add_u32 v178, s19, 8, v1
	v_ashrrev_i32_e32 v167, 31, v166
	v_lshlrev_b64 v[204:205], 1, v[166:167]
	v_ashrrev_i32_e32 v179, 31, v178
	v_lshl_add_u64 v[176:177], s[4:5], 0, v[204:205]
	v_lshlrev_b64 v[206:207], 11, v[178:179]
	v_lshl_add_u64 v[132:133], v[176:177], 0, v[206:207]
	global_load_dwordx4 v[196:199], v[132:133], off
	global_load_dwordx4 v[200:203], v[132:133], off offset:256
	v_or_b32_e32 v188, 16, v178
	v_or_b32_e32 v184, 32, v178
	v_or_b32_e32 v180, 48, v178
	v_ashrrev_i32_e32 v189, 31, v188
	v_ashrrev_i32_e32 v185, 31, v184
	v_ashrrev_i32_e32 v181, 31, v180
	v_lshlrev_b64 v[190:191], 11, v[188:189]
	v_lshlrev_b64 v[186:187], 11, v[184:185]
	v_lshlrev_b64 v[182:183], 11, v[180:181]
	v_lshl_add_u64 v[132:133], v[176:177], 0, v[190:191]
	v_lshl_add_u64 v[134:135], v[176:177], 0, v[186:187]
	v_lshl_add_u64 v[208:209], v[176:177], 0, v[182:183]
	global_load_dwordx4 v[152:155], v[132:133], off
	global_load_dwordx4 v[148:151], v[132:133], off offset:256
	global_load_dwordx4 v[144:147], v[134:135], off
	global_load_dwordx4 v[140:143], v[134:135], off offset:256
	global_load_dwordx4 v[136:139], v[208:209], off
	s_nop 0
	global_load_dwordx4 v[132:135], v[208:209], off offset:256
	v_add_u32_e32 v250, 0x80, v178
	v_ashrrev_i32_e32 v251, 31, v250
	v_lshlrev_b64 v[250:251], 11, v[250:251]
	v_lshl_add_u64 v[250:251], v[176:177], 0, v[250:251]
	global_load_dwordx4 v[234:237], v[250:251], off
	global_load_dwordx4 v[238:241], v[250:251], off offset:256
	s_mov_b32 s70, 0x8000
	s_mov_b32 s71, 0
	v_lshl_add_u64 v[250:251], v[250:251], 0, s[70:71]
	global_load_dwordx4 v[242:245], v[250:251], off
	global_load_dwordx4 v[246:249], v[250:251], off offset:256
	v_and_b32_e32 v208, 64, v218
	v_xor_b32_e32 v195, 16, v218
	v_add_u32_e32 v208, 64, v208
	v_xor_b32_e32 v209, 32, v218
	v_cmp_lt_i32_e32 vcc, v195, v208
	v_lshl_add_u64 v[206:207], s[4:5], 0, v[206:207]
	v_lshl_add_u64 v[204:205], v[206:207], 0, v[204:205]
	v_cndmask_b32_e32 v195, v218, v195, vcc
	v_cmp_lt_i32_e32 vcc, v209, v208
	v_lshlrev_b32_e32 v195, 2, v195
	s_ashr_i32 s19, s18, 31
	v_cndmask_b32_e32 v225, v218, v209, vcc
	s_waitcnt vmcnt(0)
	v_lshlrev_b32_e32 v206, 16, v196
	v_and_b32_e32 v207, 0xffff0000, v196
	v_lshlrev_b32_e32 v196, 16, v197
	v_and_b32_e32 v197, 0xffff0000, v197
	v_lshlrev_b32_e32 v208, 16, v198
	v_and_b32_e32 v209, 0xffff0000, v198
	v_lshlrev_b32_e32 v198, 16, v199
	v_and_b32_e32 v199, 0xffff0000, v199
	v_lshlrev_b32_e32 v210, 16, v200
	v_and_b32_e32 v211, 0xffff0000, v200
	v_lshlrev_b32_e32 v200, 16, v201
	v_and_b32_e32 v201, 0xffff0000, v201
	v_lshlrev_b32_e32 v212, 16, v202
	v_and_b32_e32 v213, 0xffff0000, v202
	v_lshlrev_b32_e32 v202, 16, v203
	v_and_b32_e32 v203, 0xffff0000, v203
	v_pk_add_f32 v[130:131], v[130:131], v[196:197]
	v_pk_add_f32 v[128:129], v[128:129], v[206:207]
	v_pk_add_f32 v[126:127], v[126:127], v[198:199]
	v_pk_add_f32 v[124:125], v[124:125], v[208:209]
	v_pk_add_f32 v[122:123], v[122:123], v[200:201]
	v_pk_add_f32 v[120:121], v[120:121], v[210:211]
	v_pk_add_f32 v[196:197], v[118:119], v[202:203]
	v_pk_add_f32 v[198:199], v[116:117], v[212:213]
	v_mul_f32_e32 v118, v129, v129
	v_mul_f32_e32 v119, v131, v131
	v_mul_f32_e32 v200, v125, v125
	v_mul_f32_e32 v201, v127, v127
	v_cvt_pk_bf16_f32 v116, v128, v129
	v_cvt_pk_bf16_f32 v117, v130, v131
	v_mul_f32_e32 v129, v121, v121
	v_mul_f32_e32 v131, v123, v123
	v_mul_f32_e32 v202, v199, v199
	v_mul_f32_e32 v203, v197, v197
	v_fmac_f32_e32 v118, v128, v128
	v_fmac_f32_e32 v119, v130, v130
	v_fmac_f32_e32 v200, v124, v124
	v_fmac_f32_e32 v201, v126, v126
	v_fmac_f32_e32 v129, v120, v120
	v_fmac_f32_e32 v131, v122, v122
	v_fmac_f32_e32 v202, v198, v198
	v_fmac_f32_e32 v203, v196, v196
	v_add_f32_e32 v118, v118, v119
	v_add_f32_e32 v119, v200, v201
	v_add_f32_e32 v128, v129, v131
	v_add_f32_e32 v129, v202, v203
	v_add_f32_e32 v118, v118, v119
	v_add_f32_e32 v119, v128, v129
	v_add_f32_e32 v128, v118, v119
	ds_bpermute_b32 v129, v195, v128
	v_cvt_pk_bf16_f32 v118, v124, v125
	v_cvt_pk_bf16_f32 v119, v126, v127
	global_store_dwordx4 v[204:205], v[116:119], off
	v_cvt_pk_bf16_f32 v120, v120, v121
	v_cvt_pk_bf16_f32 v121, v122, v123
	v_cvt_pk_bf16_f32 v122, v198, v199
	v_cvt_pk_bf16_f32 v123, v196, v197
	global_store_dwordx4 v[204:205], v[120:123], off offset:256
	s_waitcnt lgkmcnt(0)
	v_add_f32_e32 v117, v128, v129
	v_lshlrev_b32_e32 v116, 2, v225
	ds_bpermute_b32 v118, v116, v117
	s_and_saveexec_b64 s[14:15], s[42:43]
	s_cbranch_execz .LBB0_779
	v_lshl_add_u64 v[120:121], v[178:179], 4, s[6:7]
	v_lshl_add_u64 v[120:121], s[18:19], 2, v[120:121]
	s_waitcnt lgkmcnt(0)
	v_add_f32_e32 v117, v117, v118
	global_atomic_add_f32 v[120:121], v117, off

.LBB0_785:
	s_or_b64 exec, exec, s[14:15]
	v_add_u32_e32 v104, 0x80, v178
	v_ashrrev_i32_e32 v105, 31, v104
	v_lshlrev_b64 v[114:115], 11, v[104:105]
	s_waitcnt lgkmcnt(0)
	v_lshl_add_u64 v[68:69], v[176:177], 0, v[114:115]
	v_add_u32_e32 v100, 0x90, v178
	v_add_u32_e32 v96, 0xa0, v178
	v_add_u32_e32 v92, 0xb0, v178
	v_ashrrev_i32_e32 v101, 31, v100
	v_ashrrev_i32_e32 v97, 31, v96
	v_ashrrev_i32_e32 v93, 31, v92
	v_lshlrev_b64 v[102:103], 11, v[100:101]
	v_lshlrev_b64 v[98:99], 11, v[96:97]
	v_lshlrev_b64 v[94:95], 11, v[92:93]
	v_lshl_add_u64 v[68:69], v[176:177], 0, v[102:103]
	v_lshl_add_u64 v[70:71], v[176:177], 0, v[98:99]
	v_lshl_add_u64 v[118:119], v[176:177], 0, v[94:95]
	global_load_dwordx4 v[80:83], v[70:71], off
	global_load_dwordx4 v[76:79], v[70:71], off offset:256
	global_load_dwordx4 v[72:75], v[118:119], off
	s_nop 0
	global_load_dwordx4 v[68:71], v[118:119], off offset:256
	v_mov_b64_e32 v[106:107], v[234:235]
	v_mov_b64_e32 v[108:109], v[236:237]
	v_mov_b64_e32 v[110:111], v[238:239]
	v_mov_b64_e32 v[112:113], v[240:241]
	v_mov_b64_e32 v[88:89], v[242:243]
	v_mov_b64_e32 v[90:91], v[244:245]
	v_mov_b64_e32 v[84:85], v[246:247]
	v_mov_b64_e32 v[86:87], v[248:249]
	s_waitcnt vmcnt(7)
	v_lshlrev_b32_e32 v118, 16, v106
	v_and_b32_e32 v119, 0xffff0000, v106
	v_lshlrev_b32_e32 v106, 16, v107
	v_and_b32_e32 v107, 0xffff0000, v107
	v_lshlrev_b32_e32 v120, 16, v108
	v_and_b32_e32 v121, 0xffff0000, v108
	v_lshlrev_b32_e32 v108, 16, v109
	v_and_b32_e32 v109, 0xffff0000, v109
	s_waitcnt vmcnt(6)
	v_lshlrev_b32_e32 v122, 16, v110
	v_and_b32_e32 v123, 0xffff0000, v110
	v_lshlrev_b32_e32 v110, 16, v111
	v_and_b32_e32 v111, 0xffff0000, v111
	v_lshlrev_b32_e32 v124, 16, v112
	v_and_b32_e32 v125, 0xffff0000, v112
	v_lshlrev_b32_e32 v112, 16, v113
	v_and_b32_e32 v113, 0xffff0000, v113
	v_pk_add_f32 v[66:67], v[66:67], v[106:107]
	v_pk_add_f32 v[64:65], v[64:65], v[118:119]
	v_pk_add_f32 v[62:63], v[62:63], v[108:109]
	v_pk_add_f32 v[60:61], v[60:61], v[120:121]
	v_pk_add_f32 v[58:59], v[58:59], v[110:111]
	v_pk_add_f32 v[56:57], v[56:57], v[122:123]
	v_pk_add_f32 v[106:107], v[54:55], v[112:113]
	v_pk_add_f32 v[108:109], v[52:53], v[124:125]
	v_mul_f32_e32 v110, v65, v65
	v_mul_f32_e32 v111, v67, v67
	v_mul_f32_e32 v112, v61, v61
	v_mul_f32_e32 v113, v63, v63
	v_cvt_pk_bf16_f32 v52, v64, v65
	v_cvt_pk_bf16_f32 v53, v66, v67
	v_cvt_pk_bf16_f32 v54, v60, v61
	v_cvt_pk_bf16_f32 v55, v62, v63
	v_mul_f32_e32 v61, v57, v57
	v_mul_f32_e32 v63, v59, v59
	v_mul_f32_e32 v65, v109, v109
	v_mul_f32_e32 v67, v107, v107
	v_fmac_f32_e32 v110, v64, v64
	v_fmac_f32_e32 v111, v66, v66
	v_fmac_f32_e32 v112, v60, v60
	v_fmac_f32_e32 v113, v62, v62
	v_fmac_f32_e32 v61, v56, v56
	v_fmac_f32_e32 v63, v58, v58
	v_fmac_f32_e32 v65, v108, v108
	v_fmac_f32_e32 v67, v106, v106
	v_add_f32_e32 v60, v110, v111
	v_add_f32_e32 v62, v112, v113
	v_add_f32_e32 v61, v61, v63
	v_add_f32_e32 v63, v65, v67
	v_add_f32_e32 v60, v60, v62
	v_add_f32_e32 v61, v61, v63
	v_add_f32_e32 v62, v60, v61
	ds_bpermute_b32 v63, v195, v62
	v_lshl_add_u64 v[60:61], s[4:5], 0, v[114:115]
	v_lshl_add_u64 v[60:61], v[166:167], 1, v[60:61]
	global_store_dwordx4 v[60:61], v[52:55], off
	s_waitcnt lgkmcnt(0)
	s_nop 0
	v_add_f32_e32 v52, v62, v63
	ds_bpermute_b32 v53, v116, v52
	v_cvt_pk_bf16_f32 v54, v56, v57
	v_cvt_pk_bf16_f32 v55, v58, v59
	v_cvt_pk_bf16_f32 v56, v108, v109
	v_cvt_pk_bf16_f32 v57, v106, v107
	global_store_dwordx4 v[60:61], v[54:57], off offset:256
	s_and_saveexec_b64 s[14:15], s[42:43]
	s_cbranch_execz .LBB0_787
	v_lshl_add_u64 v[54:55], v[104:105], 4, s[6:7]
	v_lshl_add_u64 v[54:55], s[18:19], 2, v[54:55]
	s_waitcnt lgkmcnt(0)
	v_add_f32_e32 v52, v52, v53
	global_atomic_add_f32 v[54:55], v52, off

.LBB0_1002:
	v_lshl_add_u32 v182, s49, 8, v1
	v_lshl_or_b32 v178, s48, 8, v195
	v_ashrrev_i32_e32 v179, 31, v178
	v_ashrrev_i32_e32 v183, 31, v182
	v_lshl_add_u64 v[180:181], v[178:179], 1, s[24:25]
	v_lshlrev_b64 v[132:133], 11, v[182:183]
	v_or_b32_e32 v188, 16, v182
	v_lshl_add_u64 v[132:133], v[180:181], 0, v[132:133]
	v_ashrrev_i32_e32 v189, 31, v188
	global_load_dwordx4 v[198:201], v[132:133], off
	global_load_dwordx4 v[156:159], v[132:133], off offset:256
	v_lshlrev_b64 v[132:133], 11, v[188:189]
	v_or_b32_e32 v186, 32, v182
	v_lshl_add_u64 v[132:133], v[180:181], 0, v[132:133]
	v_ashrrev_i32_e32 v187, 31, v186
	global_load_dwordx4 v[152:155], v[132:133], off
	global_load_dwordx4 v[148:151], v[132:133], off offset:256
	v_lshlrev_b64 v[132:133], 11, v[186:187]
	v_or_b32_e32 v184, 48, v182
	v_lshl_add_u64 v[132:133], v[180:181], 0, v[132:133]
	v_ashrrev_i32_e32 v185, 31, v184
	global_load_dwordx4 v[144:147], v[132:133], off
	global_load_dwordx4 v[140:143], v[132:133], off offset:256
	v_lshlrev_b64 v[132:133], 11, v[184:185]
	v_lshl_add_u64 v[132:133], v[180:181], 0, v[132:133]
	global_load_dwordx4 v[136:139], v[132:133], off
	s_nop 0
	global_load_dwordx4 v[132:135], v[132:133], off offset:256
	v_add_u32_e32 v250, 0x80, v182
	v_ashrrev_i32_e32 v251, 31, v250
	v_lshlrev_b64 v[250:251], 11, v[250:251]
	v_lshl_add_u64 v[250:251], v[180:181], 0, v[250:251]
	global_load_dwordx4 v[234:237], v[250:251], off
	global_load_dwordx4 v[238:241], v[250:251], off offset:256
	s_mov_b32 s70, 0x8000
	s_mov_b32 s71, 0
	v_lshl_add_u64 v[250:251], v[250:251], 0, s[70:71]
	global_load_dwordx4 v[242:245], v[250:251], off
	global_load_dwordx4 v[246:249], v[250:251], off offset:256
	v_cndmask_b32_e64 v190, 0, 1, s[44:45]
	v_cmp_ne_u32_e64 s[4:5], 1, v190
	v_lshlrev_b64 v[190:191], 10, v[182:183]
	v_lshl_add_u64 v[190:191], v[190:191], 0, v[178:179]
	s_andn2_b64 vcc, exec, s[44:45]
	s_waitcnt vmcnt(0)
	v_lshlrev_b32_e32 v192, 16, v198
	v_and_b32_e32 v193, 0xffff0000, v198
	v_lshlrev_b32_e32 v198, 16, v199
	v_and_b32_e32 v199, 0xffff0000, v199
	v_lshlrev_b32_e32 v202, 16, v200
	v_and_b32_e32 v203, 0xffff0000, v200
	v_lshlrev_b32_e32 v200, 16, v201
	v_and_b32_e32 v201, 0xffff0000, v201
	v_pk_add_f32 v[130:131], v[130:131], v[198:199]
	v_pk_add_f32 v[128:129], v[128:129], v[192:193]
	v_pk_add_f32 v[126:127], v[126:127], v[200:201]
	v_pk_add_f32 v[124:125], v[124:125], v[202:203]
	v_lshl_add_u64 v[192:193], v[190:191], 2, s[22:23]
	s_cbranch_vccnz .LBB0_1004
	global_store_dwordx4 v[192:193], v[128:131], off
	global_store_dwordx4 v[192:193], v[124:127], off offset:16

.LBB0_1046:
	v_add_u32_e32 v102, 0x80, v182
	v_ashrrev_i32_e32 v103, 31, v102
	v_lshlrev_b64 v[68:69], 11, v[102:103]
	v_add_u32_e32 v100, 0x90, v182
	v_lshl_add_u64 v[68:69], v[180:181], 0, v[68:69]
	v_ashrrev_i32_e32 v101, 31, v100
	v_lshlrev_b64 v[68:69], 11, v[100:101]
	v_add_u32_e32 v98, 0xa0, v182
	v_lshl_add_u64 v[68:69], v[180:181], 0, v[68:69]
	v_ashrrev_i32_e32 v99, 31, v98
	v_lshlrev_b64 v[68:69], 11, v[98:99]
	v_add_u32_e32 v96, 0xb0, v182
	v_lshl_add_u64 v[68:69], v[180:181], 0, v[68:69]
	v_ashrrev_i32_e32 v97, 31, v96
	global_load_dwordx4 v[80:83], v[68:69], off
	global_load_dwordx4 v[76:79], v[68:69], off offset:256
	v_lshlrev_b64 v[68:69], 11, v[96:97]
	v_lshl_add_u64 v[68:69], v[180:181], 0, v[68:69]
	s_waitcnt lgkmcnt(0)
	global_load_dwordx4 v[72:75], v[68:69], off
	s_nop 0
	global_load_dwordx4 v[68:71], v[68:69], off offset:256
	v_mov_b64_e32 v[106:107], v[234:235]
	v_mov_b64_e32 v[108:109], v[236:237]
	v_mov_b64_e32 v[92:93], v[238:239]
	v_mov_b64_e32 v[94:95], v[240:241]
	v_mov_b64_e32 v[88:89], v[242:243]
	v_mov_b64_e32 v[90:91], v[244:245]
	v_mov_b64_e32 v[84:85], v[246:247]
	v_mov_b64_e32 v[86:87], v[248:249]
	v_lshlrev_b64 v[104:105], 10, v[102:103]
	v_lshl_add_u64 v[104:105], v[104:105], 0, v[178:179]
	s_and_b64 vcc, exec, s[4:5]
	s_waitcnt vmcnt(7)
	v_lshlrev_b32_e32 v110, 16, v106
	v_and_b32_e32 v111, 0xffff0000, v106
	v_lshlrev_b32_e32 v106, 16, v107
	v_and_b32_e32 v107, 0xffff0000, v107
	v_lshlrev_b32_e32 v112, 16, v108
	v_and_b32_e32 v113, 0xffff0000, v108
	v_lshlrev_b32_e32 v108, 16, v109
	v_and_b32_e32 v109, 0xffff0000, v109
	v_pk_add_f32 v[66:67], v[66:67], v[106:107]
	v_pk_add_f32 v[64:65], v[64:65], v[110:111]
	v_pk_add_f32 v[62:63], v[62:63], v[108:109]
	v_pk_add_f32 v[60:61], v[60:61], v[112:113]
	v_lshl_add_u64 v[106:107], v[104:105], 2, s[22:23]
	s_cbranch_vccnz .LBB0_1048
	global_store_dwordx4 v[106:107], v[64:67], off
	global_store_dwordx4 v[106:107], v[60:63], off offset:16
